# prompt attention PV: the transposed V reads of each 32-key tile issued together (4 operand sets) with counted lgkmcnt instead of read-wait-MFMA per step
# baseline (speedup 1.0000x reference)
; #define LAS __attribute__((address_space(3)))
; #define MFMA32(a, b, c) __builtin_amdgcn_mfma_f32_32x32x16_bf16((a), (b), (c), 0, 0, 0)
; __device__ __forceinline__ void attn_run(LAS unsigned char* lds, const Params& p, const bf16_t* P, bf16_t* Y, float* ssa, int l, int t0, int t1, int wave) {
;     ...
;             for (int T = 0; T < 6; ++T)
;                 if (T >= T0) {
;                     const int prow = 64 * ((T >> 1) == 0 ? sl0 : ((T >> 1) == 1 ? sl1 : sl2)) + 32 * (T & 1);
; #pragma unroll
;                     for (int s = 0; s < 2; ++s) {
;                         const bf16x8 xs = pack_step(st[T], s);
; #pragma unroll
;                         for (int dt = 0; dt < 2; ++dt) {
;                             const LAS bf16_t* vp = VT + (prow + 16 * s + 4 * h + ((lane & 15) >> 2)) * 72 + 32 * dt + 16 * ((lane >> 4) & 1) + 4 * (lane & 3);
;                             const s16x4 lo = __builtin_amdgcn_ds_read_tr16_b64_v4i16((LAS s16x4*)vp), hi = __builtin_amdgcn_ds_read_tr16_b64_v4i16((LAS s16x4*)(vp + 8 * 72));
;                             const bf16x8 pa = __builtin_shufflevector(lo, hi, 0, 1, 2, 3, 4, 5, 6, 7);
;                             o[dt] = MFMA32(pa, xs, o[dt]);
;                         }
;                     }
.LBB0_350:
	v_add_u32_e32 v0, s29, v169
	v_mad_u64_u32 v[10:11], s[12:13], v0, s89, v[158:159]
	ds_read_b64_tr_b16 v[6:7], v10 offset:27648
	ds_read_b64_tr_b16 v[8:9], v10 offset:28800
	ds_read_b64_tr_b16 v[234:235], v10 offset:27712
	ds_read_b64_tr_b16 v[236:237], v10 offset:28864
	ds_read_b64_tr_b16 v[238:239], v10 offset:29952
	ds_read_b64_tr_b16 v[240:241], v10 offset:31104
	ds_read_b64_tr_b16 v[242:243], v10 offset:30016
	ds_read_b64_tr_b16 v[244:245], v10 offset:31168
	v_cvt_pk_bf16_f32 v2, v179, v193
	v_cvt_pk_bf16_f32 v3, v198, v202
	v_cvt_pk_bf16_f32 v4, v213, v220
	v_cvt_pk_bf16_f32 v5, v225, v227
	s_waitcnt lgkmcnt(6)
	s_nop 0
	v_mfma_f32_32x32x16_bf16 v[32:47], v[6:9], v[2:5], v[32:47]
	s_waitcnt lgkmcnt(4)
	v_mfma_f32_32x32x16_bf16 v[16:31], v[234:237], v[2:5], v[16:31]
	v_cvt_pk_bf16_f32 v2, v180, v194
	v_cvt_pk_bf16_f32 v3, v199, v203
	v_cvt_pk_bf16_f32 v4, v214, v221
	v_cvt_pk_bf16_f32 v5, v226, v228
	s_waitcnt lgkmcnt(2)
	s_nop 0
	v_mfma_f32_32x32x16_bf16 v[32:47], v[238:241], v[2:5], v[32:47]
	s_waitcnt lgkmcnt(0)
	v_mfma_f32_32x32x16_bf16 v[16:31], v[242:245], v[2:5], v[16:31]

; #define LAS __attribute__((address_space(3)))
; __device__ __forceinline__ unsigned pk2(float lo, float hi) { const f32x2 v = {lo, hi}; return __builtin_bit_cast(unsigned, __builtin_convertvector(v, bf16x2_t)); }
; __device__ __forceinline__ void attn_run(LAS unsigned char* lds, const Params& p, const bf16_t* P, bf16_t* Y, float* ssa, int l, int t0, int t1, int wave) {
;     ...
;             for (int T = 0; T < 6; ++T)
;                 if (T >= T0) {
;                     const int prow = 64 * ((T >> 1) == 0 ? sl0 : ((T >> 1) == 1 ? sl1 : sl2)) + 32 * (T & 1);
; #pragma unroll
;                     for (int s = 0; s < 2; ++s) {
;                         const bf16x8 xs = pack_step(st[T], s);
; #pragma unroll
;                         for (int dt = 0; dt < 2; ++dt) {
;                             const LAS bf16_t* vp = VT + (prow + 16 * s + 4 * h + ((lane & 15) >> 2)) * 72 + 32 * dt + 16 * ((lane >> 4) & 1) + 4 * (lane & 3);
;                             const s16x4 lo = __builtin_amdgcn_ds_read_tr16_b64_v4i16((LAS s16x4*)vp), hi = __builtin_amdgcn_ds_read_tr16_b64_v4i16((LAS s16x4*)(vp + 8 * 72));
;                             const bf16x8 pa = __builtin_shufflevector(lo, hi, 0, 1, 2, 3, 4, 5, 6, 7);
;                             o[dt] = MFMA32(pa, xs, o[dt]);
;                         }
;                     }
;                 }
;             float ss = 0.f;
;             bf16_t* yp = Y + qrow * DM + head * 64 + 8 * h;
; #pragma unroll
;             for (int dt = 0; dt < 2; ++dt)
; #pragma unroll
;                 for (int pr = 0; pr < 2; ++pr) {
;                     float a[4], bq[4];
; #pragma unroll
;                     for (int k = 0; k < 4; ++k) { a[k] = o[dt][8 * pr + k] * inv; bq[k] = o[dt][8 * pr + 4 + k] * inv; }
;                     ss += ((a[0] * a[0] + a[1] * a[1]) + (a[2] * a[2] + a[3] * a[3])) + ((bq[0] * bq[0] + bq[1] * bq[1]) + (bq[2] * bq[2] + bq[3] * bq[3]));
; #pragma unroll
;                     for (int k = 0; k < 4; ++k) swap_halves(a[k], bq[k]);
;                     const u32x4 gw = gwv[2 * dt + pr];
;                     u32x4 w; w.x = pk2(a[0] * bf_lo(gw.x), a[1] * bf_hi(gw.x)); w.y = pk2(a[2] * bf_lo(gw.y), a[3] * bf_hi(gw.y));
;                     w.z = pk2(bq[0] * bf_lo(gw.z), bq[1] * bf_hi(gw.z)); w.w = pk2(bq[2] * bf_lo(gw.w), bq[3] * bf_hi(gw.w));
;                     *(u32x4*)(yp + 32 * dt + 16 * pr) = w;
.LBB0_353:
	v_add_u32_e32 v0, s26, v169
	v_mad_u64_u32 v[10:11], s[12:13], v0, s89, v[158:159]
	ds_read_b64_tr_b16 v[6:7], v10 offset:27648
	ds_read_b64_tr_b16 v[8:9], v10 offset:28800
	ds_read_b64_tr_b16 v[234:235], v10 offset:27712
	ds_read_b64_tr_b16 v[236:237], v10 offset:28864
	ds_read_b64_tr_b16 v[238:239], v10 offset:29952
	ds_read_b64_tr_b16 v[240:241], v10 offset:31104
	ds_read_b64_tr_b16 v[242:243], v10 offset:30016
	ds_read_b64_tr_b16 v[244:245], v10 offset:31168
	v_cvt_pk_bf16_f32 v2, v94, v97
	v_cvt_pk_bf16_f32 v3, v174, v181
	v_cvt_pk_bf16_f32 v4, v200, v204
	v_cvt_pk_bf16_f32 v5, v208, v215
	s_waitcnt lgkmcnt(6)
	s_nop 0
	v_mfma_f32_32x32x16_bf16 v[32:47], v[6:9], v[2:5], v[32:47]
	s_waitcnt lgkmcnt(4)
	v_mfma_f32_32x32x16_bf16 v[16:31], v[234:237], v[2:5], v[16:31]
	v_cvt_pk_bf16_f32 v2, v95, v163
	v_cvt_pk_bf16_f32 v3, v175, v182
	v_cvt_pk_bf16_f32 v4, v201, v205
	v_cvt_pk_bf16_f32 v5, v209, v216
	s_waitcnt lgkmcnt(2)
	s_nop 0
	v_mfma_f32_32x32x16_bf16 v[32:47], v[238:241], v[2:5], v[32:47]
	s_waitcnt lgkmcnt(0)
	v_mfma_f32_32x32x16_bf16 v[16:31], v[242:245], v[2:5], v[16:31]
.LBB0_354:
	v_add_u32_e32 v6, s25, v168
	v_sub_f32_e32 v2, v66, v68
	v_mad_u64_u32 v[10:11], s[12:13], v6, s89, v[158:159]
	v_exp_f32_e32 v2, v2
	ds_read_b64_tr_b16 v[6:7], v10 offset:27648
	ds_read_b64_tr_b16 v[8:9], v10 offset:28800
	s_waitcnt lgkmcnt(2)
	v_add_f32_e32 v0, v69, v70
	v_cvt_pk_bf16_f32 v3, v63, v79
	v_add_f32_e32 v0, v2, v0
	v_cvt_pk_bf16_f32 v2, v56, v60
	v_cvt_pk_bf16_f32 v4, v144, v145
	v_cvt_pk_bf16_f32 v5, v142, v143
	s_lshl_b32 s44, s10, 1
	s_waitcnt lgkmcnt(0)
	v_mfma_f32_32x32x16_bf16 v[32:47], v[6:9], v[2:5], v[32:47]
	ds_read_b64_tr_b16 v[6:7], v10 offset:27712
	ds_read_b64_tr_b16 v[8:9], v10 offset:28864
	ds_read_b64_tr_b16 v[234:235], v10 offset:29952
	ds_read_b64_tr_b16 v[236:237], v10 offset:31104
	ds_read_b64_tr_b16 v[238:239], v10 offset:30016
	ds_read_b64_tr_b16 v[240:241], v10 offset:31168
	s_waitcnt lgkmcnt(4)
	v_mfma_f32_32x32x16_bf16 v[16:31], v[6:9], v[2:5], v[16:31]
	v_cvt_pk_bf16_f32 v2, v59, v64
	v_cvt_pk_bf16_f32 v3, v78, v96
	v_cvt_pk_bf16_f32 v4, v92, v93
	v_cvt_pk_bf16_f32 v5, v90, v91
	s_waitcnt lgkmcnt(2)
	s_nop 0
	v_mfma_f32_32x32x16_bf16 v[32:47], v[234:237], v[2:5], v[32:47]
	s_waitcnt lgkmcnt(0)
	v_mfma_f32_32x32x16_bf16 v[16:31], v[238:241], v[2:5], v[16:31]
	v_add_u32_e32 v6, s25, v169
	v_mad_u64_u32 v[10:11], s[12:13], v6, s89, v[158:159]
	ds_read_b64_tr_b16 v[6:7], v10 offset:27648
	ds_read_b64_tr_b16 v[8:9], v10 offset:28800
	ds_read_b64_tr_b16 v[234:235], v10 offset:27712
	ds_read_b64_tr_b16 v[236:237], v10 offset:28864
	ds_read_b64_tr_b16 v[238:239], v10 offset:29952
	ds_read_b64_tr_b16 v[240:241], v10 offset:31104
	ds_read_b64_tr_b16 v[242:243], v10 offset:30016
	ds_read_b64_tr_b16 v[244:245], v10 offset:31168
	v_cvt_pk_bf16_f32 v2, v52, v54
	v_cvt_pk_bf16_f32 v3, v57, v61
	v_cvt_pk_bf16_f32 v4, v81, v84
	v_cvt_pk_bf16_f32 v5, v82, v83
	s_waitcnt lgkmcnt(6)
	s_nop 0
	v_mfma_f32_32x32x16_bf16 v[32:47], v[6:9], v[2:5], v[32:47]
	s_waitcnt lgkmcnt(4)
	v_mfma_f32_32x32x16_bf16 v[16:31], v[234:237], v[2:5], v[16:31]
	v_cvt_pk_bf16_f32 v2, v48, v49
	v_cvt_pk_bf16_f32 v3, v51, v53
	v_cvt_pk_bf16_f32 v4, v58, v62
	v_cvt_pk_bf16_f32 v5, v65, v67
	s_waitcnt lgkmcnt(2)
	s_nop 0
	v_mfma_f32_32x32x16_bf16 v[32:47], v[238:241], v[2:5], v[32:47]
	s_waitcnt lgkmcnt(0)
	v_mfma_f32_32x32x16_bf16 v[16:31], v[242:245], v[2:5], v[16:31]
	v_div_scale_f32 v2, s[12:13], v0, v0, 1.0
	v_rcp_f32_e32 v3, v2
	s_nop 0
	v_fma_f32 v4, -v2, v3, 1.0
	v_fmac_f32_e32 v3, v4, v3
	v_div_scale_f32 v4, vcc, 1.0, v0, 1.0
	v_mul_f32_e32 v5, v4, v3
	v_fma_f32 v6, -v2, v5, v4
	v_fmac_f32_e32 v5, v6, v3
	v_fma_f32 v2, -v2, v5, v4
	v_div_fmas_f32 v2, v2, v3, v5
	v_div_fixup_f32 v0, v2, v0, 1.0
	v_mul_f32_e32 v5, v0, v33
	v_mul_f32_e32 v9, v0, v35
	v_mul_f32_e32 v4, v0, v32
	v_mul_f32_e32 v8, v0, v34
	v_mul_f32_e32 v12, v5, v5
	v_mul_f32_e32 v13, v9, v9
	v_mul_f32_e32 v7, v0, v37
	v_mul_f32_e32 v11, v0, v39
	v_fmac_f32_e32 v12, v4, v4
	v_fmac_f32_e32 v13, v8, v8
	v_mul_f32_e32 v6, v0, v36
	v_mul_f32_e32 v10, v0, v38
	v_add_f32_e32 v12, v12, v13
	v_mul_f32_e32 v13, v7, v7
	v_mul_f32_e32 v14, v11, v11
	v_fmac_f32_e32 v13, v6, v6
	v_fmac_f32_e32 v14, v10, v10
	v_add_f32_e32 v13, v13, v14
	v_permlane32_swap_b32_e32 v4, v6
	v_permlane32_swap_b32_e32 v5, v7
	v_add_f32_e32 v14, v13, v12
	v_permlane32_swap_b32_e32 v8, v10
	v_permlane32_swap_b32_e32 v9, v11
	v_lshlrev_b32_e32 v12, 16, v134
	v_and_b32_e32 v13, 0xffff0000, v134
	v_pk_mul_f32 v[4:5], v[12:13], v[4:5]
	v_lshlrev_b32_e32 v12, 16, v135
	v_and_b32_e32 v13, 0xffff0000, v135
	v_pk_mul_f32 v[8:9], v[12:13], v[8:9]
	v_lshlrev_b64 v[2:3], 12, v[164:165]
	v_cvt_pk_bf16_f32 v4, v4, v5
	v_cvt_pk_bf16_f32 v5, v8, v9
	v_lshlrev_b32_e32 v8, 16, v136
	v_and_b32_e32 v9, 0xffff0000, v136
	v_lshl_add_u64 v[2:3], s[36:37], 0, v[2:3]
	v_pk_mul_f32 v[6:7], v[8:9], v[6:7]
	v_lshlrev_b32_e32 v8, 16, v137
	v_and_b32_e32 v9, 0xffff0000, v137
	v_lshl_add_u64 v[2:3], v[2:3], 0, s[44:45]
	v_pk_mul_f32 v[8:9], v[8:9], v[10:11]
	v_lshl_add_u64 v[2:3], v[156:157], 1, v[2:3]
	v_cvt_pk_bf16_f32 v6, v6, v7
	v_cvt_pk_bf16_f32 v7, v8, v9
	global_store_dwordx4 v[2:3], v[4:7], off
	v_mul_f32_e32 v9, v0, v43
	v_mul_f32_e32 v8, v0, v42
	v_mul_f32_e32 v5, v0, v41
	v_mul_f32_e32 v4, v0, v40
	v_mul_f32_e32 v12, v5, v5
	v_mul_f32_e32 v13, v9, v9
; #define LAS __attribute__((address_space(3)))
; __device__ __forceinline__ unsigned pk2(float lo, float hi) { const f32x2 v = {lo, hi}; return __builtin_bit_cast(unsigned, __builtin_convertvector(v, bf16x2_t)); }
; __device__ __forceinline__ void attn_run(LAS unsigned char* lds, const Params& p, const bf16_t* P, bf16_t* Y, float* ssa, int l, int t0, int t1, int wave) {
;     ...
;             for (int T = 0; T < 6; ++T)
;                 if (T >= T0) {
;                     const int prow = 64 * ((T >> 1) == 0 ? sl0 : ((T >> 1) == 1 ? sl1 : sl2)) + 32 * (T & 1);
; #pragma unroll
;                     for (int s = 0; s < 2; ++s) {
;                         const bf16x8 xs = pack_step(st[T], s);
; #pragma unroll
;                         for (int dt = 0; dt < 2; ++dt) {
;                             const LAS bf16_t* vp = VT + (prow + 16 * s + 4 * h + ((lane & 15) >> 2)) * 72 + 32 * dt + 16 * ((lane >> 4) & 1) + 4 * (lane & 3);
;                             const s16x4 lo = __builtin_amdgcn_ds_read_tr16_b64_v4i16((LAS s16x4*)vp), hi = __builtin_amdgcn_ds_read_tr16_b64_v4i16((LAS s16x4*)(vp + 8 * 72));
;                             const bf16x8 pa = __builtin_shufflevector(lo, hi, 0, 1, 2, 3, 4, 5, 6, 7);
;                             o[dt] = MFMA32(pa, xs, o[dt]);
;                         }
;                     }
;     ...
; #pragma unroll
;             for (int dt = 0; dt < 2; ++dt)
; #pragma unroll
;                 for (int pr = 0; pr < 2; ++pr) {
;                     float a[4], bq[4];
; #pragma unroll
;                     for (int k = 0; k < 4; ++k) { a[k] = o[dt][8 * pr + k] * inv; bq[k] = o[dt][8 * pr + 4 + k] * inv; }
;                     ss += ((a[0] * a[0] + a[1] * a[1]) + (a[2] * a[2] + a[3] * a[3])) + ((bq[0] * bq[0] + bq[1] * bq[1]) + (bq[2] * bq[2] + bq[3] * bq[3]));
; #pragma unroll
;                     for (int k = 0; k < 4; ++k) swap_halves(a[k], bq[k]);
;                     const u32x4 gw = gwv[2 * dt + pr];
;                     u32x4 w; w.x = pk2(a[0] * bf_lo(gw.x), a[1] * bf_hi(gw.x)); w.y = pk2(a[2] * bf_lo(gw.y), a[3] * bf_hi(gw.y));
;                     w.z = pk2(bq[0] * bf_lo(gw.z), bq[1] * bf_hi(gw.z)); w.w = pk2(bq[2] * bf_lo(gw.w), bq[3] * bf_hi(gw.w));
;                     *(u32x4*)(yp + 32 * dt + 16 * pr) = w;
;                 }
;             ss += __shfl_xor(ss, 32);
;             if (h == 0) ssa[qrow * 16 + head] = ss;
	v_mul_f32_e32 v7, v0, v45
	v_mul_f32_e32 v11, v0, v47
	v_fmac_f32_e32 v12, v4, v4
	v_fmac_f32_e32 v13, v8, v8
	v_mul_f32_e32 v6, v0, v44
	v_mul_f32_e32 v10, v0, v46
	v_add_f32_e32 v12, v12, v13
	v_mul_f32_e32 v13, v7, v7
	v_mul_f32_e32 v15, v11, v11
	v_fmac_f32_e32 v13, v6, v6
	v_fmac_f32_e32 v15, v10, v10
	v_add_f32_e32 v13, v13, v15
	v_add_f32_e32 v12, v13, v12
	v_permlane32_swap_b32_e32 v4, v6
	v_permlane32_swap_b32_e32 v5, v7
	v_permlane32_swap_b32_e32 v8, v10
	v_permlane32_swap_b32_e32 v9, v11
	v_add_f32_e32 v14, v14, v12
	v_lshlrev_b32_e32 v12, 16, v130
	v_and_b32_e32 v13, 0xffff0000, v130
	v_pk_mul_f32 v[4:5], v[12:13], v[4:5]
	v_lshlrev_b32_e32 v12, 16, v131
	v_and_b32_e32 v13, 0xffff0000, v131
	v_pk_mul_f32 v[8:9], v[12:13], v[8:9]
	v_cvt_pk_bf16_f32 v4, v4, v5
	v_cvt_pk_bf16_f32 v5, v8, v9
	v_lshlrev_b32_e32 v8, 16, v132
	v_and_b32_e32 v9, 0xffff0000, v132
	v_pk_mul_f32 v[6:7], v[8:9], v[6:7]
	v_lshlrev_b32_e32 v8, 16, v133
	v_and_b32_e32 v9, 0xffff0000, v133
	v_pk_mul_f32 v[8:9], v[8:9], v[10:11]
	v_cvt_pk_bf16_f32 v6, v6, v7
	v_cvt_pk_bf16_f32 v7, v8, v9
	global_store_dwordx4 v[2:3], v[4:7], off offset:32
	v_mul_f32_e32 v9, v0, v19
	v_mul_f32_e32 v8, v0, v18
	v_mul_f32_e32 v5, v0, v17
	v_mul_f32_e32 v4, v0, v16
	v_mul_f32_e32 v12, v5, v5
	v_mul_f32_e32 v13, v9, v9
	v_mul_f32_e32 v7, v0, v21
	v_mul_f32_e32 v11, v0, v23
	v_fmac_f32_e32 v12, v4, v4
	v_fmac_f32_e32 v13, v8, v8
	v_mul_f32_e32 v6, v0, v20
	v_mul_f32_e32 v10, v0, v22
	v_add_f32_e32 v12, v12, v13
	v_mul_f32_e32 v13, v7, v7
	v_mul_f32_e32 v15, v11, v11
	v_fmac_f32_e32 v13, v6, v6
	v_fmac_f32_e32 v15, v10, v10
	v_add_f32_e32 v13, v13, v15
	v_add_f32_e32 v12, v13, v12
	v_permlane32_swap_b32_e32 v4, v6
	v_permlane32_swap_b32_e32 v5, v7
	v_permlane32_swap_b32_e32 v8, v10
	v_permlane32_swap_b32_e32 v9, v11
	v_add_f32_e32 v14, v14, v12
	v_lshlrev_b32_e32 v12, 16, v126
	v_and_b32_e32 v13, 0xffff0000, v126
	v_pk_mul_f32 v[4:5], v[12:13], v[4:5]
	v_lshlrev_b32_e32 v12, 16, v127
	v_and_b32_e32 v13, 0xffff0000, v127
	v_pk_mul_f32 v[8:9], v[12:13], v[8:9]
	v_cvt_pk_bf16_f32 v4, v4, v5
	v_cvt_pk_bf16_f32 v5, v8, v9
	v_lshlrev_b32_e32 v8, 16, v128
	v_and_b32_e32 v9, 0xffff0000, v128
	v_pk_mul_f32 v[6:7], v[8:9], v[6:7]
	v_lshlrev_b32_e32 v8, 16, v129
	v_and_b32_e32 v9, 0xffff0000, v129
	v_pk_mul_f32 v[8:9], v[8:9], v[10:11]
	v_cvt_pk_bf16_f32 v6, v6, v7
	v_cvt_pk_bf16_f32 v7, v8, v9
	global_store_dwordx4 v[2:3], v[4:7], off offset:64
	v_mul_f32_e32 v9, v0, v27
	v_mul_f32_e32 v8, v0, v26
	v_mul_f32_e32 v5, v0, v25
	v_mul_f32_e32 v4, v0, v24
	v_mul_f32_e32 v6, v0, v28
	v_mul_f32_e32 v7, v0, v29
	v_mul_f32_e32 v10, v0, v30
	v_mul_f32_e32 v11, v0, v31
	v_mul_f32_e32 v0, v5, v5
	v_mul_f32_e32 v12, v9, v9
	v_fmac_f32_e32 v0, v4, v4
	v_fmac_f32_e32 v12, v8, v8
	v_add_f32_e32 v0, v0, v12
	v_mul_f32_e32 v12, v7, v7
	v_mul_f32_e32 v13, v11, v11
	v_fmac_f32_e32 v12, v6, v6
	v_fmac_f32_e32 v13, v10, v10
	v_add_f32_e32 v12, v12, v13
	v_permlane32_swap_b32_e32 v4, v6
	v_permlane32_swap_b32_e32 v5, v7
	v_add_f32_e32 v0, v12, v0
	v_permlane32_swap_b32_e32 v8, v10
	v_permlane32_swap_b32_e32 v9, v11
	v_lshlrev_b32_e32 v12, 16, v122
	v_and_b32_e32 v13, 0xffff0000, v122
	v_pk_mul_f32 v[4:5], v[12:13], v[4:5]
	v_lshlrev_b32_e32 v12, 16, v123
	v_and_b32_e32 v13, 0xffff0000, v123
	v_pk_mul_f32 v[8:9], v[12:13], v[8:9]
	v_cvt_pk_bf16_f32 v4, v4, v5
	v_cvt_pk_bf16_f32 v5, v8, v9
	v_lshlrev_b32_e32 v8, 16, v124
	v_and_b32_e32 v9, 0xffff0000, v124
	v_pk_mul_f32 v[6:7], v[8:9], v[6:7]
	v_lshlrev_b32_e32 v8, 16, v125
	v_and_b32_e32 v9, 0xffff0000, v125
	v_pk_mul_f32 v[8:9], v[8:9], v[10:11]
	v_add_f32_e32 v0, v0, v14
	v_cvt_pk_bf16_f32 v6, v6, v7
	v_cvt_pk_bf16_f32 v7, v8, v9
	global_store_dwordx4 v[2:3], v[4:7], off offset:96
	ds_bpermute_b32 v2, v167, v0
	s_and_saveexec_b64 s[10:11], s[40:41]
	s_cbranch_execz .LBB0_324
	v_readlane_b32 s4, v253, 15
	v_lshlrev_b64 v[4:5], 6, v[164:165]
	v_readlane_b32 s5, v253, 16
	s_lshl_b32 s44, s24, 2
	s_waitcnt lgkmcnt(0)
	v_add_f32_e32 v0, v0, v2
	v_lshl_add_u64 v[4:5], s[4:5], 0, v[4:5]
	v_lshl_add_u64 v[4:5], v[4:5], 0, s[44:45]
	global_store_dword v[4:5], v0, off
	s_branch .LBB0_324
.LBB0_356:
	v_add_u32_e32 v0, s26, v168
	v_mad_u64_u32 v[10:11], s[10:11], v0, s89, v[158:159]
	ds_read_b64_tr_b16 v[6:7], v10 offset:27648
	ds_read_b64_tr_b16 v[8:9], v10 offset:28800
	ds_read_b64_tr_b16 v[234:235], v10 offset:27712
	ds_read_b64_tr_b16 v[236:237], v10 offset:28864
	ds_read_b64_tr_b16 v[238:239], v10 offset:29952
	ds_read_b64_tr_b16 v[240:241], v10 offset:31104
	ds_read_b64_tr_b16 v[242:243], v10 offset:30016
	ds_read_b64_tr_b16 v[244:245], v10 offset:31168
	v_cvt_pk_bf16_f32 v2, v172, v177
	v_cvt_pk_bf16_f32 v3, v183, v196
	v_cvt_pk_bf16_f32 v4, v206, v211
	v_cvt_pk_bf16_f32 v5, v218, v223
	s_waitcnt lgkmcnt(6)
	s_nop 0
	v_mfma_f32_32x32x16_bf16 v[32:47], v[6:9], v[2:5], v[32:47]
	s_waitcnt lgkmcnt(4)
	v_mfma_f32_32x32x16_bf16 v[16:31], v[234:237], v[2:5], v[16:31]
	v_cvt_pk_bf16_f32 v2, v173, v178
	v_cvt_pk_bf16_f32 v3, v192, v197
	v_cvt_pk_bf16_f32 v4, v207, v212
	v_cvt_pk_bf16_f32 v5, v219, v224
	s_waitcnt lgkmcnt(2)
	s_nop 0
	v_mfma_f32_32x32x16_bf16 v[32:47], v[238:241], v[2:5], v[32:47]
	s_waitcnt lgkmcnt(0)
	v_mfma_f32_32x32x16_bf16 v[16:31], v[242:245], v[2:5], v[16:31]
	s_and_b64 vcc, exec, s[46:47]
	s_lshl_b32 s10, s24, 6
	s_cbranch_vccz .LBB0_353
	s_branch .LBB0_354

; #define LAS __attribute__((address_space(3)))
; #define MFMA32(a, b, c) __builtin_amdgcn_mfma_f32_32x32x16_bf16((a), (b), (c), 0, 0, 0)
; __device__ __forceinline__ void attn_run(LAS unsigned char* lds, const Params& p, const bf16_t* P, bf16_t* Y, float* ssa, int l, int t0, int t1, int wave) {
;     ...
;             f32x16 o[2];
; #pragma unroll
;             for (int e = 0; e < 16; ++e) { o[0][e] = 0.f; o[1][e] = 0.f; }
; #pragma unroll
;             for (int T = 0; T < 6; ++T)
;                 if (T >= T0) {
;                     const int prow = 64 * ((T >> 1) == 0 ? sl0 : ((T >> 1) == 1 ? sl1 : sl2)) + 32 * (T & 1);
; #pragma unroll
;                     for (int s = 0; s < 2; ++s) {
;                         const bf16x8 xs = pack_step(st[T], s);
; #pragma unroll
;                         for (int dt = 0; dt < 2; ++dt) {
;                             const LAS bf16_t* vp = VT + (prow + 16 * s + 4 * h + ((lane & 15) >> 2)) * 72 + 32 * dt + 16 * ((lane >> 4) & 1) + 4 * (lane & 3);
;                             const s16x4 lo = __builtin_amdgcn_ds_read_tr16_b64_v4i16((LAS s16x4*)vp), hi = __builtin_amdgcn_ds_read_tr16_b64_v4i16((LAS s16x4*)(vp + 8 * 72));
;                             const bf16x8 pa = __builtin_shufflevector(lo, hi, 0, 1, 2, 3, 4, 5, 6, 7);
;                             o[dt] = MFMA32(pa, xs, o[dt]);
;                         }
;                     }
.LBB0_360:
	v_add_u32_e32 v0, s29, v168
	v_mad_u64_u32 v[10:11], s[12:13], v0, s89, v[158:159]
	ds_read_b64_tr_b16 v[6:7], v10 offset:27648
	ds_read_b64_tr_b16 v[8:9], v10 offset:28800
	v_cvt_pk_bf16_f32 v2, v50, v75
	v_cvt_pk_bf16_f32 v3, v76, v77
	v_cvt_pk_bf16_f32 v4, v80, v171
	v_cvt_pk_bf16_f32 v5, v176, v195
	s_waitcnt lgkmcnt(0)
	s_nop 0
	v_mfma_f32_32x32x16_bf16 v[32:47], v[6:9], v[2:5], 0
	ds_read_b64_tr_b16 v[6:7], v10 offset:27712
	ds_read_b64_tr_b16 v[8:9], v10 offset:28864
	s_waitcnt lgkmcnt(0)
	v_mfma_f32_32x32x16_bf16 v[16:31], v[6:9], v[2:5], 0
	ds_read_b64_tr_b16 v[6:7], v10 offset:29952
	ds_read_b64_tr_b16 v[8:9], v10 offset:31104
	ds_read_b64_tr_b16 v[234:235], v10 offset:30016
	ds_read_b64_tr_b16 v[236:237], v10 offset:31168
	v_cvt_pk_bf16_f32 v2, v55, v210
	v_cvt_pk_bf16_f32 v3, v217, v222
	v_cvt_pk_bf16_f32 v4, v229, v230
	v_cvt_pk_bf16_f32 v5, v231, v232
	s_waitcnt lgkmcnt(2)
	s_nop 0
	v_mfma_f32_32x32x16_bf16 v[32:47], v[6:9], v[2:5], v[32:47]
	s_waitcnt lgkmcnt(0)
	v_mfma_f32_32x32x16_bf16 v[16:31], v[234:237], v[2:5], v[16:31]
	s_and_b64 vcc, exec, s[42:43]
	s_cbranch_vccnz .LBB0_351
	s_branch .LBB0_350

; #define LAS __attribute__((address_space(3)))
; #define MFMA32(a, b, c) __builtin_amdgcn_mfma_f32_32x32x16_bf16((a), (b), (c), 0, 0, 0)
; __device__ __forceinline__ void attn_run(LAS unsigned char* lds, const Params& p, const bf16_t* P, bf16_t* Y, float* ssa, int l, int t0, int t1, int wave) {
;     ...
;             for (int T = 0; T < 6; ++T)
;                 if (T >= T0) {
;                     const int prow = 64 * ((T >> 1) == 0 ? sl0 : ((T >> 1) == 1 ? sl1 : sl2)) + 32 * (T & 1);
; #pragma unroll
;                     for (int s = 0; s < 2; ++s) {
;                         const bf16x8 xs = pack_step(st[T], s);
; #pragma unroll
;                         for (int dt = 0; dt < 2; ++dt) {
;                             const LAS bf16_t* vp = VT + (prow + 16 * s + 4 * h + ((lane & 15) >> 2)) * 72 + 32 * dt + 16 * ((lane >> 4) & 1) + 4 * (lane & 3);
;                             const s16x4 lo = __builtin_amdgcn_ds_read_tr16_b64_v4i16((LAS s16x4*)vp), hi = __builtin_amdgcn_ds_read_tr16_b64_v4i16((LAS s16x4*)(vp + 8 * 72));
;                             const bf16x8 pa = __builtin_shufflevector(lo, hi, 0, 1, 2, 3, 4, 5, 6, 7);
;                             o[dt] = MFMA32(pa, xs, o[dt]);
;                         }
;                     }
.LBB0_435:
	v_add_u32_e32 v0, s26, v169
	v_mad_u64_u32 v[10:11], s[12:13], v0, s89, v[158:159]
	ds_read_b64_tr_b16 v[6:7], v10 offset:27648
	ds_read_b64_tr_b16 v[8:9], v10 offset:28800
	ds_read_b64_tr_b16 v[234:235], v10 offset:27712
	ds_read_b64_tr_b16 v[236:237], v10 offset:28864
	ds_read_b64_tr_b16 v[238:239], v10 offset:29952
	ds_read_b64_tr_b16 v[240:241], v10 offset:31104
	ds_read_b64_tr_b16 v[242:243], v10 offset:30016
	ds_read_b64_tr_b16 v[244:245], v10 offset:31168
	v_cvt_pk_bf16_f32 v2, v179, v193
	v_cvt_pk_bf16_f32 v3, v198, v202
	v_cvt_pk_bf16_f32 v4, v213, v220
	v_cvt_pk_bf16_f32 v5, v225, v227
	s_waitcnt lgkmcnt(6)
	s_nop 0
	v_mfma_f32_32x32x16_bf16 v[32:47], v[6:9], v[2:5], v[32:47]
	s_waitcnt lgkmcnt(4)
	v_mfma_f32_32x32x16_bf16 v[16:31], v[234:237], v[2:5], v[16:31]
	v_cvt_pk_bf16_f32 v2, v180, v194
	v_cvt_pk_bf16_f32 v3, v199, v203
	v_cvt_pk_bf16_f32 v4, v214, v221
	v_cvt_pk_bf16_f32 v5, v226, v228
	s_waitcnt lgkmcnt(2)
	s_nop 0
	v_mfma_f32_32x32x16_bf16 v[32:47], v[238:241], v[2:5], v[32:47]
	s_waitcnt lgkmcnt(0)
	v_mfma_f32_32x32x16_bf16 v[16:31], v[242:245], v[2:5], v[16:31]

; #define LAS __attribute__((address_space(3)))
; #define MFMA32(a, b, c) __builtin_amdgcn_mfma_f32_32x32x16_bf16((a), (b), (c), 0, 0, 0)
; __device__ __forceinline__ void attn_run(LAS unsigned char* lds, const Params& p, const bf16_t* P, bf16_t* Y, float* ssa, int l, int t0, int t1, int wave) {
;     ...
;             for (int T = 0; T < 6; ++T)
;                 if (T >= T0) {
;                     const int prow = 64 * ((T >> 1) == 0 ? sl0 : ((T >> 1) == 1 ? sl1 : sl2)) + 32 * (T & 1);
; #pragma unroll
;                     for (int s = 0; s < 2; ++s) {
;                         const bf16x8 xs = pack_step(st[T], s);
; #pragma unroll
;                         for (int dt = 0; dt < 2; ++dt) {
;                             const LAS bf16_t* vp = VT + (prow + 16 * s + 4 * h + ((lane & 15) >> 2)) * 72 + 32 * dt + 16 * ((lane >> 4) & 1) + 4 * (lane & 3);
;                             const s16x4 lo = __builtin_amdgcn_ds_read_tr16_b64_v4i16((LAS s16x4*)vp), hi = __builtin_amdgcn_ds_read_tr16_b64_v4i16((LAS s16x4*)(vp + 8 * 72));
;                             const bf16x8 pa = __builtin_shufflevector(lo, hi, 0, 1, 2, 3, 4, 5, 6, 7);
;                             o[dt] = MFMA32(pa, xs, o[dt]);
;                         }
;                     }
;                 }
;             float ss = 0.f;
;             bf16_t* yp = Y + qrow * DM + head * 64 + 8 * h;
; #pragma unroll
;             for (int dt = 0; dt < 2; ++dt)
; #pragma unroll
;                 for (int pr = 0; pr < 2; ++pr) {
;                     float a[4], bq[4];
; #pragma unroll
;                     for (int k = 0; k < 4; ++k) { a[k] = o[dt][8 * pr + k] * inv; bq[k] = o[dt][8 * pr + 4 + k] * inv; }
;                     ss += ((a[0] * a[0] + a[1] * a[1]) + (a[2] * a[2] + a[3] * a[3])) + ((bq[0] * bq[0] + bq[1] * bq[1]) + (bq[2] * bq[2] + bq[3] * bq[3]));
; #pragma unroll
;                     for (int k = 0; k < 4; ++k) swap_halves(a[k], bq[k]);
;                     const u32x4 gw = gwv[2 * dt + pr];
;                     u32x4 w; w.x = pk2(a[0] * bf_lo(gw.x), a[1] * bf_hi(gw.x)); w.y = pk2(a[2] * bf_lo(gw.y), a[3] * bf_hi(gw.y));
;                     w.z = pk2(bq[0] * bf_lo(gw.z), bq[1] * bf_hi(gw.z)); w.w = pk2(bq[2] * bf_lo(gw.w), bq[3] * bf_hi(gw.w));
;                     *(u32x4*)(yp + 32 * dt + 16 * pr) = w;
;                 }
.LBB0_438:
	v_add_u32_e32 v0, s25, v169
	v_mad_u64_u32 v[10:11], s[12:13], v0, s89, v[158:159]
	ds_read_b64_tr_b16 v[6:7], v10 offset:27648
	ds_read_b64_tr_b16 v[8:9], v10 offset:28800
	ds_read_b64_tr_b16 v[234:235], v10 offset:27712
	ds_read_b64_tr_b16 v[236:237], v10 offset:28864
	ds_read_b64_tr_b16 v[238:239], v10 offset:29952
	ds_read_b64_tr_b16 v[240:241], v10 offset:31104
	ds_read_b64_tr_b16 v[242:243], v10 offset:30016
	ds_read_b64_tr_b16 v[244:245], v10 offset:31168
	v_cvt_pk_bf16_f32 v2, v94, v97
	v_cvt_pk_bf16_f32 v3, v174, v181
	v_cvt_pk_bf16_f32 v4, v200, v204
	v_cvt_pk_bf16_f32 v5, v208, v215
	s_waitcnt lgkmcnt(6)
	s_nop 0
	v_mfma_f32_32x32x16_bf16 v[32:47], v[6:9], v[2:5], v[32:47]
	s_waitcnt lgkmcnt(4)
	v_mfma_f32_32x32x16_bf16 v[16:31], v[234:237], v[2:5], v[16:31]
	v_cvt_pk_bf16_f32 v2, v95, v163
	v_cvt_pk_bf16_f32 v3, v175, v182
	v_cvt_pk_bf16_f32 v4, v201, v205
	v_cvt_pk_bf16_f32 v5, v209, v216
	s_waitcnt lgkmcnt(2)
	s_nop 0
	v_mfma_f32_32x32x16_bf16 v[32:47], v[238:241], v[2:5], v[32:47]
	s_waitcnt lgkmcnt(0)
	v_mfma_f32_32x32x16_bf16 v[16:31], v[242:245], v[2:5], v[16:31]
.LBB0_439:
	v_add_u32_e32 v6, s24, v168
	v_sub_f32_e32 v2, v66, v68
	v_mad_u64_u32 v[10:11], s[12:13], v6, s89, v[158:159]
	v_exp_f32_e32 v2, v2
	ds_read_b64_tr_b16 v[6:7], v10 offset:27648
	ds_read_b64_tr_b16 v[8:9], v10 offset:28800
	s_waitcnt lgkmcnt(2)
	v_add_f32_e32 v0, v69, v70
	v_cvt_pk_bf16_f32 v3, v63, v79
	v_add_f32_e32 v0, v2, v0
	v_cvt_pk_bf16_f32 v2, v56, v60
	v_cvt_pk_bf16_f32 v4, v144, v145
	v_cvt_pk_bf16_f32 v5, v142, v143
	s_lshl_b32 s44, s10, 1
	s_waitcnt lgkmcnt(0)
	v_mfma_f32_32x32x16_bf16 v[32:47], v[6:9], v[2:5], v[32:47]
	ds_read_b64_tr_b16 v[6:7], v10 offset:27712
	ds_read_b64_tr_b16 v[8:9], v10 offset:28864
	ds_read_b64_tr_b16 v[234:235], v10 offset:29952
	ds_read_b64_tr_b16 v[236:237], v10 offset:31104
	ds_read_b64_tr_b16 v[238:239], v10 offset:30016
	ds_read_b64_tr_b16 v[240:241], v10 offset:31168
	s_waitcnt lgkmcnt(4)
	v_mfma_f32_32x32x16_bf16 v[16:31], v[6:9], v[2:5], v[16:31]
	v_cvt_pk_bf16_f32 v2, v59, v64
	v_cvt_pk_bf16_f32 v3, v78, v96
	v_cvt_pk_bf16_f32 v4, v92, v93
	v_cvt_pk_bf16_f32 v5, v90, v91
	s_waitcnt lgkmcnt(2)
	s_nop 0
	v_mfma_f32_32x32x16_bf16 v[32:47], v[234:237], v[2:5], v[32:47]
	s_waitcnt lgkmcnt(0)
	v_mfma_f32_32x32x16_bf16 v[16:31], v[238:241], v[2:5], v[16:31]
	v_add_u32_e32 v6, s24, v169
	v_mad_u64_u32 v[10:11], s[12:13], v6, s89, v[158:159]
	ds_read_b64_tr_b16 v[6:7], v10 offset:27648
	ds_read_b64_tr_b16 v[8:9], v10 offset:28800
	ds_read_b64_tr_b16 v[234:235], v10 offset:27712
	ds_read_b64_tr_b16 v[236:237], v10 offset:28864
	ds_read_b64_tr_b16 v[238:239], v10 offset:29952
	ds_read_b64_tr_b16 v[240:241], v10 offset:31104
	ds_read_b64_tr_b16 v[242:243], v10 offset:30016
	ds_read_b64_tr_b16 v[244:245], v10 offset:31168
	v_cvt_pk_bf16_f32 v2, v52, v54
	v_cvt_pk_bf16_f32 v3, v57, v61
	v_cvt_pk_bf16_f32 v4, v81, v84
	v_cvt_pk_bf16_f32 v5, v82, v83
	s_waitcnt lgkmcnt(6)
	s_nop 0
	v_mfma_f32_32x32x16_bf16 v[32:47], v[6:9], v[2:5], v[32:47]
	s_waitcnt lgkmcnt(4)
	v_mfma_f32_32x32x16_bf16 v[16:31], v[234:237], v[2:5], v[16:31]
	v_cvt_pk_bf16_f32 v2, v48, v49
	v_cvt_pk_bf16_f32 v3, v51, v53
	v_cvt_pk_bf16_f32 v4, v58, v62
	v_cvt_pk_bf16_f32 v5, v65, v67
	s_waitcnt lgkmcnt(2)
	s_nop 0
	v_mfma_f32_32x32x16_bf16 v[32:47], v[238:241], v[2:5], v[32:47]
	s_waitcnt lgkmcnt(0)
	v_mfma_f32_32x32x16_bf16 v[16:31], v[242:245], v[2:5], v[16:31]
	v_div_scale_f32 v2, s[12:13], v0, v0, 1.0
	v_rcp_f32_e32 v3, v2
	s_nop 0
	v_fma_f32 v4, -v2, v3, 1.0
	v_fmac_f32_e32 v3, v4, v3
	v_div_scale_f32 v4, vcc, 1.0, v0, 1.0
	v_mul_f32_e32 v5, v4, v3
	v_fma_f32 v6, -v2, v5, v4
	v_fmac_f32_e32 v5, v6, v3
	v_fma_f32 v2, -v2, v5, v4
	v_div_fmas_f32 v2, v2, v3, v5
	v_div_fixup_f32 v0, v2, v0, 1.0
	v_mul_f32_e32 v5, v0, v33
	v_mul_f32_e32 v9, v0, v35
	v_mul_f32_e32 v4, v0, v32
	v_mul_f32_e32 v8, v0, v34
	v_mul_f32_e32 v12, v5, v5
	v_mul_f32_e32 v13, v9, v9
	v_mul_f32_e32 v7, v0, v37
	v_mul_f32_e32 v11, v0, v39
	v_fmac_f32_e32 v12, v4, v4
	v_fmac_f32_e32 v13, v8, v8
	v_mul_f32_e32 v6, v0, v36
	v_mul_f32_e32 v10, v0, v38
	v_add_f32_e32 v12, v12, v13
	v_mul_f32_e32 v13, v7, v7
	v_mul_f32_e32 v14, v11, v11
	v_fmac_f32_e32 v13, v6, v6
	v_fmac_f32_e32 v14, v10, v10
	v_add_f32_e32 v13, v13, v14
	v_permlane32_swap_b32_e32 v4, v6
	v_permlane32_swap_b32_e32 v5, v7
	v_add_f32_e32 v14, v13, v12
	v_permlane32_swap_b32_e32 v8, v10
	v_permlane32_swap_b32_e32 v9, v11
	v_lshlrev_b32_e32 v12, 16, v134
	v_and_b32_e32 v13, 0xffff0000, v134
	v_pk_mul_f32 v[4:5], v[12:13], v[4:5]
	v_lshlrev_b32_e32 v12, 16, v135
	v_and_b32_e32 v13, 0xffff0000, v135
	v_pk_mul_f32 v[8:9], v[12:13], v[8:9]
	v_lshlrev_b64 v[2:3], 12, v[164:165]
	v_cvt_pk_bf16_f32 v4, v4, v5
	v_cvt_pk_bf16_f32 v5, v8, v9
	v_lshlrev_b32_e32 v8, 16, v136
	v_and_b32_e32 v9, 0xffff0000, v136
	v_lshl_add_u64 v[2:3], s[36:37], 0, v[2:3]
	v_pk_mul_f32 v[6:7], v[8:9], v[6:7]
	v_lshlrev_b32_e32 v8, 16, v137
	v_and_b32_e32 v9, 0xffff0000, v137
	v_lshl_add_u64 v[2:3], v[2:3], 0, s[44:45]
	v_pk_mul_f32 v[8:9], v[8:9], v[10:11]
	v_lshl_add_u64 v[2:3], v[156:157], 1, v[2:3]
	v_cvt_pk_bf16_f32 v6, v6, v7
	v_cvt_pk_bf16_f32 v7, v8, v9
	global_store_dwordx4 v[2:3], v[4:7], off
	v_mul_f32_e32 v9, v0, v43
	v_mul_f32_e32 v8, v0, v42
	v_mul_f32_e32 v5, v0, v41
	v_mul_f32_e32 v4, v0, v40
	v_mul_f32_e32 v12, v5, v5
	v_mul_f32_e32 v13, v9, v9
; #define LAS __attribute__((address_space(3)))
; __device__ __forceinline__ void attn_run(LAS unsigned char* lds, const Params& p, const bf16_t* P, bf16_t* Y, float* ssa, int l, int t0, int t1, int wave) {
;     ...
;             for (int T = 0; T < 6; ++T)
;                 if (T >= T0) {
;                     const int prow = 64 * ((T >> 1) == 0 ? sl0 : ((T >> 1) == 1 ? sl1 : sl2)) + 32 * (T & 1);
; #pragma unroll
;                     for (int s = 0; s < 2; ++s) {
;                         const bf16x8 xs = pack_step(st[T], s);
; #pragma unroll
;                         for (int dt = 0; dt < 2; ++dt) {
;                             const LAS bf16_t* vp = VT + (prow + 16 * s + 4 * h + ((lane & 15) >> 2)) * 72 + 32 * dt + 16 * ((lane >> 4) & 1) + 4 * (lane & 3);
;                             const s16x4 lo = __builtin_amdgcn_ds_read_tr16_b64_v4i16((LAS s16x4*)vp), hi = __builtin_amdgcn_ds_read_tr16_b64_v4i16((LAS s16x4*)(vp + 8 * 72));
;                             const bf16x8 pa = __builtin_shufflevector(lo, hi, 0, 1, 2, 3, 4, 5, 6, 7);
;                             o[dt] = MFMA32(pa, xs, o[dt]);
;                         }
;                     }
;                 }
;             float ss = 0.f;
;             bf16_t* yp = Y + qrow * DM + head * 64 + 8 * h;
; #pragma unroll
;             for (int dt = 0; dt < 2; ++dt)
; #pragma unroll
;                 for (int pr = 0; pr < 2; ++pr) {
;                     float a[4], bq[4];
; #pragma unroll
;                     for (int k = 0; k < 4; ++k) { a[k] = o[dt][8 * pr + k] * inv; bq[k] = o[dt][8 * pr + 4 + k] * inv; }
;                     ss += ((a[0] * a[0] + a[1] * a[1]) + (a[2] * a[2] + a[3] * a[3])) + ((bq[0] * bq[0] + bq[1] * bq[1]) + (bq[2] * bq[2] + bq[3] * bq[3]));
; #pragma unroll
;                     for (int k = 0; k < 4; ++k) swap_halves(a[k], bq[k]);
;                     const u32x4 gw = gwv[2 * dt + pr];
;                     u32x4 w; w.x = pk2(a[0] * bf_lo(gw.x), a[1] * bf_hi(gw.x)); w.y = pk2(a[2] * bf_lo(gw.y), a[3] * bf_hi(gw.y));
;                     w.z = pk2(bq[0] * bf_lo(gw.z), bq[1] * bf_hi(gw.z)); w.w = pk2(bq[2] * bf_lo(gw.w), bq[3] * bf_hi(gw.w));
;                     *(u32x4*)(yp + 32 * dt + 16 * pr) = w;
;                 }
;             ss += __shfl_xor(ss, 32);
;             if (h == 0) ssa[qrow * 16 + head] = ss;
	v_mul_f32_e32 v7, v0, v45
	v_mul_f32_e32 v11, v0, v47
	v_fmac_f32_e32 v12, v4, v4
	v_fmac_f32_e32 v13, v8, v8
	v_mul_f32_e32 v6, v0, v44
	v_mul_f32_e32 v10, v0, v46
	v_add_f32_e32 v12, v12, v13
	v_mul_f32_e32 v13, v7, v7
	v_mul_f32_e32 v15, v11, v11
	v_fmac_f32_e32 v13, v6, v6
	v_fmac_f32_e32 v15, v10, v10
	v_add_f32_e32 v13, v13, v15
	v_add_f32_e32 v12, v13, v12
	v_permlane32_swap_b32_e32 v4, v6
	v_permlane32_swap_b32_e32 v5, v7
	v_permlane32_swap_b32_e32 v8, v10
	v_permlane32_swap_b32_e32 v9, v11
	v_add_f32_e32 v14, v14, v12
	v_lshlrev_b32_e32 v12, 16, v130
	v_and_b32_e32 v13, 0xffff0000, v130
	v_pk_mul_f32 v[4:5], v[12:13], v[4:5]
	v_lshlrev_b32_e32 v12, 16, v131
	v_and_b32_e32 v13, 0xffff0000, v131
	v_pk_mul_f32 v[8:9], v[12:13], v[8:9]
	v_cvt_pk_bf16_f32 v4, v4, v5
	v_cvt_pk_bf16_f32 v5, v8, v9
	v_lshlrev_b32_e32 v8, 16, v132
	v_and_b32_e32 v9, 0xffff0000, v132
	v_pk_mul_f32 v[6:7], v[8:9], v[6:7]
	v_lshlrev_b32_e32 v8, 16, v133
	v_and_b32_e32 v9, 0xffff0000, v133
	v_pk_mul_f32 v[8:9], v[8:9], v[10:11]
	v_cvt_pk_bf16_f32 v6, v6, v7
	v_cvt_pk_bf16_f32 v7, v8, v9
	global_store_dwordx4 v[2:3], v[4:7], off offset:32
	v_mul_f32_e32 v9, v0, v19
	v_mul_f32_e32 v8, v0, v18
	v_mul_f32_e32 v5, v0, v17
	v_mul_f32_e32 v4, v0, v16
	v_mul_f32_e32 v12, v5, v5
	v_mul_f32_e32 v13, v9, v9
	v_mul_f32_e32 v7, v0, v21
	v_mul_f32_e32 v11, v0, v23
	v_fmac_f32_e32 v12, v4, v4
	v_fmac_f32_e32 v13, v8, v8
	v_mul_f32_e32 v6, v0, v20
	v_mul_f32_e32 v10, v0, v22
	v_add_f32_e32 v12, v12, v13
	v_mul_f32_e32 v13, v7, v7
	v_mul_f32_e32 v15, v11, v11
	v_fmac_f32_e32 v13, v6, v6
	v_fmac_f32_e32 v15, v10, v10
	v_add_f32_e32 v13, v13, v15
	v_add_f32_e32 v12, v13, v12
	v_permlane32_swap_b32_e32 v4, v6
	v_permlane32_swap_b32_e32 v5, v7
	v_permlane32_swap_b32_e32 v8, v10
	v_permlane32_swap_b32_e32 v9, v11
	v_add_f32_e32 v14, v14, v12
	v_lshlrev_b32_e32 v12, 16, v126
	v_and_b32_e32 v13, 0xffff0000, v126
	v_pk_mul_f32 v[4:5], v[12:13], v[4:5]
	v_lshlrev_b32_e32 v12, 16, v127
	v_and_b32_e32 v13, 0xffff0000, v127
	v_pk_mul_f32 v[8:9], v[12:13], v[8:9]
	v_cvt_pk_bf16_f32 v4, v4, v5
	v_cvt_pk_bf16_f32 v5, v8, v9
	v_lshlrev_b32_e32 v8, 16, v128
	v_and_b32_e32 v9, 0xffff0000, v128
	v_pk_mul_f32 v[6:7], v[8:9], v[6:7]
	v_lshlrev_b32_e32 v8, 16, v129
	v_and_b32_e32 v9, 0xffff0000, v129
	v_pk_mul_f32 v[8:9], v[8:9], v[10:11]
	v_cvt_pk_bf16_f32 v6, v6, v7
	v_cvt_pk_bf16_f32 v7, v8, v9
	global_store_dwordx4 v[2:3], v[4:7], off offset:64
	v_mul_f32_e32 v9, v0, v27
	v_mul_f32_e32 v8, v0, v26
	v_mul_f32_e32 v5, v0, v25
	v_mul_f32_e32 v4, v0, v24
	v_mul_f32_e32 v6, v0, v28
	v_mul_f32_e32 v7, v0, v29
	v_mul_f32_e32 v10, v0, v30
	v_mul_f32_e32 v11, v0, v31
	v_mul_f32_e32 v0, v5, v5
	v_mul_f32_e32 v12, v9, v9
	v_fmac_f32_e32 v0, v4, v4
	v_fmac_f32_e32 v12, v8, v8
	v_add_f32_e32 v0, v0, v12
	v_mul_f32_e32 v12, v7, v7
	v_mul_f32_e32 v13, v11, v11
	v_fmac_f32_e32 v12, v6, v6
	v_fmac_f32_e32 v13, v10, v10
	v_add_f32_e32 v12, v12, v13
	v_permlane32_swap_b32_e32 v4, v6
	v_permlane32_swap_b32_e32 v5, v7
	v_add_f32_e32 v0, v12, v0
	v_permlane32_swap_b32_e32 v8, v10
	v_permlane32_swap_b32_e32 v9, v11
	v_lshlrev_b32_e32 v12, 16, v122
	v_and_b32_e32 v13, 0xffff0000, v122
	v_pk_mul_f32 v[4:5], v[12:13], v[4:5]
	v_lshlrev_b32_e32 v12, 16, v123
	v_and_b32_e32 v13, 0xffff0000, v123
	v_pk_mul_f32 v[8:9], v[12:13], v[8:9]
	v_cvt_pk_bf16_f32 v4, v4, v5
	v_cvt_pk_bf16_f32 v5, v8, v9
	v_lshlrev_b32_e32 v8, 16, v124
	v_and_b32_e32 v9, 0xffff0000, v124
	v_pk_mul_f32 v[6:7], v[8:9], v[6:7]
	v_lshlrev_b32_e32 v8, 16, v125
	v_and_b32_e32 v9, 0xffff0000, v125
	v_pk_mul_f32 v[8:9], v[8:9], v[10:11]
	v_add_f32_e32 v0, v0, v14
	v_cvt_pk_bf16_f32 v6, v6, v7
	v_cvt_pk_bf16_f32 v7, v8, v9
	global_store_dwordx4 v[2:3], v[4:7], off offset:96
	ds_bpermute_b32 v2, v167, v0
	s_and_saveexec_b64 s[10:11], s[40:41]
	s_cbranch_execz .LBB0_409
	v_readlane_b32 s4, v253, 15
	v_lshlrev_b64 v[4:5], 6, v[164:165]
	v_readlane_b32 s5, v253, 16
	s_lshl_b32 s44, s23, 2
	s_waitcnt lgkmcnt(0)
	v_add_f32_e32 v0, v0, v2
	v_lshl_add_u64 v[4:5], s[4:5], 0, v[4:5]
	v_lshl_add_u64 v[4:5], v[4:5], 0, s[44:45]
	global_store_dword v[4:5], v0, off
	s_branch .LBB0_409
.LBB0_441:
	v_add_u32_e32 v0, s25, v168
	v_mad_u64_u32 v[10:11], s[10:11], v0, s89, v[158:159]
	ds_read_b64_tr_b16 v[6:7], v10 offset:27648
	ds_read_b64_tr_b16 v[8:9], v10 offset:28800
	ds_read_b64_tr_b16 v[234:235], v10 offset:27712
	ds_read_b64_tr_b16 v[236:237], v10 offset:28864
	ds_read_b64_tr_b16 v[238:239], v10 offset:29952
	ds_read_b64_tr_b16 v[240:241], v10 offset:31104
	ds_read_b64_tr_b16 v[242:243], v10 offset:30016
	ds_read_b64_tr_b16 v[244:245], v10 offset:31168
	v_cvt_pk_bf16_f32 v2, v172, v177
	v_cvt_pk_bf16_f32 v3, v183, v196
	v_cvt_pk_bf16_f32 v4, v206, v211
	v_cvt_pk_bf16_f32 v5, v218, v223
	s_waitcnt lgkmcnt(6)
	s_nop 0
	v_mfma_f32_32x32x16_bf16 v[32:47], v[6:9], v[2:5], v[32:47]
	s_waitcnt lgkmcnt(4)
	v_mfma_f32_32x32x16_bf16 v[16:31], v[234:237], v[2:5], v[16:31]
	v_cvt_pk_bf16_f32 v2, v173, v178
	v_cvt_pk_bf16_f32 v3, v192, v197
	v_cvt_pk_bf16_f32 v4, v207, v212
	v_cvt_pk_bf16_f32 v5, v219, v224
	s_waitcnt lgkmcnt(2)
	s_nop 0
	v_mfma_f32_32x32x16_bf16 v[32:47], v[238:241], v[2:5], v[32:47]
	s_waitcnt lgkmcnt(0)
	v_mfma_f32_32x32x16_bf16 v[16:31], v[242:245], v[2:5], v[16:31]
	s_and_b64 vcc, exec, s[46:47]
	s_lshl_b32 s10, s23, 6
	s_cbranch_vccz .LBB0_438
	s_branch .LBB0_439

; #define LAS __attribute__((address_space(3)))
; #define MFMA32(a, b, c) __builtin_amdgcn_mfma_f32_32x32x16_bf16((a), (b), (c), 0, 0, 0)
; __device__ __forceinline__ void attn_run(LAS unsigned char* lds, const Params& p, const bf16_t* P, bf16_t* Y, float* ssa, int l, int t0, int t1, int wave) {
;     ...
;             for (int T = 0; T < 6; ++T)
;                 if (T >= T0) {
;                     const int prow = 64 * ((T >> 1) == 0 ? sl0 : ((T >> 1) == 1 ? sl1 : sl2)) + 32 * (T & 1);
; #pragma unroll
;                     for (int s = 0; s < 2; ++s) {
;                         const bf16x8 xs = pack_step(st[T], s);
; #pragma unroll
;                         for (int dt = 0; dt < 2; ++dt) {
;                             const LAS bf16_t* vp = VT + (prow + 16 * s + 4 * h + ((lane & 15) >> 2)) * 72 + 32 * dt + 16 * ((lane >> 4) & 1) + 4 * (lane & 3);
;                             const s16x4 lo = __builtin_amdgcn_ds_read_tr16_b64_v4i16((LAS s16x4*)vp), hi = __builtin_amdgcn_ds_read_tr16_b64_v4i16((LAS s16x4*)(vp + 8 * 72));
;                             const bf16x8 pa = __builtin_shufflevector(lo, hi, 0, 1, 2, 3, 4, 5, 6, 7);
;                             o[dt] = MFMA32(pa, xs, o[dt]);
;                         }
;                     }
;                 }
.LBB0_445:
	v_add_u32_e32 v0, s26, v168
	v_mad_u64_u32 v[10:11], s[12:13], v0, s89, v[158:159]
	ds_read_b64_tr_b16 v[6:7], v10 offset:27648
	ds_read_b64_tr_b16 v[8:9], v10 offset:28800
	v_cvt_pk_bf16_f32 v2, v50, v75
	v_cvt_pk_bf16_f32 v3, v76, v77
	v_cvt_pk_bf16_f32 v4, v80, v171
	v_cvt_pk_bf16_f32 v5, v176, v195
	s_waitcnt lgkmcnt(0)
	s_nop 0
	v_mfma_f32_32x32x16_bf16 v[32:47], v[6:9], v[2:5], 0
	ds_read_b64_tr_b16 v[6:7], v10 offset:27712
	ds_read_b64_tr_b16 v[8:9], v10 offset:28864
	s_waitcnt lgkmcnt(0)
	v_mfma_f32_32x32x16_bf16 v[16:31], v[6:9], v[2:5], 0
	ds_read_b64_tr_b16 v[6:7], v10 offset:29952
	ds_read_b64_tr_b16 v[8:9], v10 offset:31104
	ds_read_b64_tr_b16 v[234:235], v10 offset:30016
	ds_read_b64_tr_b16 v[236:237], v10 offset:31168
	v_cvt_pk_bf16_f32 v2, v55, v210
	v_cvt_pk_bf16_f32 v3, v217, v222
	v_cvt_pk_bf16_f32 v4, v229, v230
	v_cvt_pk_bf16_f32 v5, v231, v232
	s_waitcnt lgkmcnt(2)
	s_nop 0
	v_mfma_f32_32x32x16_bf16 v[32:47], v[6:9], v[2:5], v[32:47]
	s_waitcnt lgkmcnt(0)
	v_mfma_f32_32x32x16_bf16 v[16:31], v[234:237], v[2:5], v[16:31]
	s_and_b64 vcc, exec, s[42:43]
	s_cbranch_vccnz .LBB0_436
	s_branch .LBB0_435
